# v23 + counter-free row-statistics exchange (slots preset to -1, each row polls its four slots)
# speedup vs baseline: 1.0403x; 1.0078x over previous
; __device__ __forceinline__ void xcd_barrier(const XcdBarrier& b) {
;     asm volatile("s_waitcnt vmcnt(0)" ::: "memory");
;     __syncthreads();
;     if (threadIdx.x == 0) {
;         unsigned* bar = b.bar;
;         __builtin_amdgcn_s_waitcnt(0);
;         unsigned nloc = b.st[0], nx = b.st[1];
;         if (nloc == 0u) { xcd_barrier_complete(bar, b.x, nloc, nx); b.st[0] = nloc; b.st[1] = nx; }
.LBB0_104:
	s_or_b64 exec, exec, s[14:15]
	s_load_dwordx2 s[4:5], s[0:1], 0xc8
	v_lshl_add_u32 v2, s81, 9, v0
	v_mov_b32_e32 v6, 0xbf800000
	v_cmp_gt_u32_e32 vcc, 0x10000, v2
	v_mov_b32_e32 v7, v6
	v_mov_b32_e32 v8, v6
	v_mov_b32_e32 v9, v6
	v_lshlrev_b32_e32 v2, 4, v2
	s_and_saveexec_b64 s[6:7], vcc
	s_waitcnt lgkmcnt(0)
	s_add_u32 s4, s4, 0x1f00000
	s_addc_u32 s5, s5, 0
	global_store_dwordx4 v2, v[6:9], s[4:5]
	s_or_b64 exec, exec, s[6:7]
	s_waitcnt vmcnt(0)
	s_barrier
	s_and_saveexec_b64 s[4:5], s[22:23]
	s_cbranch_execz .LBB0_156
	s_add_i32 s3, 0, 0x20160
	v_mov_b32_e32 v1, s3
	s_waitcnt vmcnt(0) expcnt(0) lgkmcnt(0)
	ds_read_b32 v3, v1
	s_add_i32 s3, 0, 0x20164
	v_mov_b32_e32 v1, s3
	ds_read_b32 v1, v1
	s_waitcnt lgkmcnt(1)
	v_cmp_ne_u32_e32 vcc, 0, v3
	s_cbranch_vccnz .LBB0_120
	v_readlane_b32 s6, v237, 0
	v_readlane_b32 s7, v237, 1
	s_load_dwordx2 s[10:11], s[6:7], 0x4
	s_add_u32 s6, s64, 0x4200
	s_addc_u32 s7, s65, 0
	s_add_u32 s8, s64, 0x4400
	s_addc_u32 s9, s65, 0
	s_waitcnt lgkmcnt(0)
	s_mul_i32 s3, s10, s33
	s_add_u32 s10, s64, 0x4500
	s_mul_i32 s3, s3, s11
	s_addc_u32 s11, s65, 0
	s_add_u32 s14, s64, 0x4600
	s_addc_u32 s15, s65, 0
	s_add_u32 s16, s64, 0x4700
	s_addc_u32 s17, s65, 0
	s_add_u32 s18, s64, 0x4800
	s_addc_u32 s19, s65, 0
	s_add_u32 s20, s64, 0x4900
	s_addc_u32 s21, s65, 0
	s_add_u32 s36, s64, 0x4a00
	s_addc_u32 s37, s65, 0
	s_add_u32 s38, s64, 0x4b00
	s_addc_u32 s39, s65, 0
	s_add_u32 s40, s64, 0x4c00
	s_addc_u32 s41, s65, 0
	s_add_u32 s42, s64, 0x4d00
	s_addc_u32 s43, s65, 0
	s_add_u32 s44, s64, 0x4e00
	s_addc_u32 s45, s65, 0
	s_add_u32 s46, s64, 0x4f00
	s_addc_u32 s47, s65, 0
	s_add_u32 s48, s64, 0x5000
	s_addc_u32 s49, s65, 0
	s_add_u32 s50, s64, 0x5100
	s_addc_u32 s51, s65, 0
	s_add_u32 s52, s64, 0x5200
	s_addc_u32 s53, s65, 0
	s_add_u32 s54, s64, 0x5300
	s_addc_u32 s55, s65, 0
	s_mov_b32 s13, 1
	v_mov_b32_e32 v17, 0
	s_branch .LBB0_108

; #define PG8_LAS __attribute__((address_space(3)))
;     __device__ __forceinline__ void operator()(const f32x4 (&acc)[2][2][4][2], const Unit& u, int wr, int wc, int fr, int fq) const {
;     ...
;         asm volatile("s_waitcnt lgkmcnt(0)" ::: "memory"); __builtin_amdgcn_s_barrier(); asm volatile("" ::: "memory");
;         const int tid = (wr * 4 + wc) * 64 + fq * 16 + fr;
;         if (tid < 256) { const f32x4 p = *(const PG8_LAS f32x4*)(P + tid * 4); __hip_atomic_store(ssq + (size_t)(u.pm * BM + tid) * 4 + u.pn, (p[0] + p[1]) + (p[2] + p[3]), __ATOMIC_RELAXED, __HIP_MEMORY_SCOPE_AGENT); }
;         asm volatile("s_waitcnt vmcnt(0)" ::: "memory"); __builtin_amdgcn_s_barrier(); asm volatile("" ::: "memory");
;         unsigned* pc = cnt + u.pm * 64;
;         if (tid == 0) __hip_atomic_fetch_add(pc, 1u, __ATOMIC_RELAXED, __HIP_MEMORY_SCOPE_AGENT);
;         if (tid < 64) { unsigned sp = 0u;
;             while (__hip_atomic_load(pc, __ATOMIC_RELAXED, __HIP_MEMORY_SCOPE_AGENT) < 4u) { __builtin_amdgcn_s_sleep(2); if (++sp > (1u << 20)) { if (tid == 0) __hip_atomic_store(tmo, 1u, __ATOMIC_RELAXED, __HIP_MEMORY_SCOPE_AGENT); break; } } }
;         asm volatile("s_waitcnt vmcnt(0)" ::: "memory"); __builtin_amdgcn_s_barrier(); asm volatile("" ::: "memory");
;         if (tid < 256) { const float* sp4 = ssq + (size_t)(u.pm * BM + tid) * 4;
;             const float t = (__hip_atomic_load(sp4, __ATOMIC_RELAXED, __HIP_MEMORY_SCOPE_AGENT) + __hip_atomic_load(sp4 + 1, __ATOMIC_RELAXED, __HIP_MEMORY_SCOPE_AGENT))
;                           + (__hip_atomic_load(sp4 + 2, __ATOMIC_RELAXED, __HIP_MEMORY_SCOPE_AGENT) + __hip_atomic_load(sp4 + 3, __ATOMIC_RELAXED, __HIP_MEMORY_SCOPE_AGENT));
;             P[1024 + tid] = 1.f / sqrtf(t * (1.f / DM) + EPS); }
.LBB0_1303:
	s_or_b64 exec, exec, s[78:79]
	s_and_saveexec_b64 s[14:15], s[12:13]
	s_cbranch_execz .LBB0_1325
	v_lshl_add_u64 v[146:147], v[146:147], 4, s[52:53]
	s_mov_b32 s24, 0x40000
.Lx7_poll:
	global_load_dword v150, v[146:147], off sc1
	global_load_dword v152, v[146:147], off offset:4 sc1
	global_load_dword v151, v[146:147], off offset:8 sc1
	global_load_dword v153, v[146:147], off offset:12 sc1
	s_waitcnt vmcnt(0)
	v_or3_b32 v149, v150, v151, v152
	v_or_b32_e32 v149, v149, v153
	v_cmp_gt_i32_e32 vcc, 0, v149
	s_cbranch_vccz .Lx7_ready
	s_sleep 1
	s_add_i32 s24, s24, -1
	s_cmp_lg_u32 s24, 0
	s_cbranch_scc1 .Lx7_poll
.Lx7_ready:
	s_mov_b32 s8, 0xf800000
	s_waitcnt vmcnt(0)
	v_pk_add_f32 v[146:147], v[150:151], v[152:153]
	s_nop 0
	v_add_f32_e32 v146, v146, v147
	v_fmamk_f32 v146, v146, 0x3a800000, v233
	v_mul_f32_e32 v147, 0x4f800000, v146
	v_cmp_gt_f32_e32 vcc, s8, v146
	s_nop 1
	v_cndmask_b32_e32 v146, v146, v147, vcc
	v_sqrt_f32_e32 v147, v146
	s_nop 0
	v_add_u32_e32 v149, -1, v147
	v_add_u32_e32 v150, 1, v147
	v_fma_f32 v151, -v149, v147, v146
	v_fma_f32 v152, -v150, v147, v146
	v_cmp_ge_f32_e64 s[12:13], 0, v151
	s_nop 1
	v_cndmask_b32_e64 v147, v147, v149, s[12:13]
	v_cmp_lt_f32_e64 s[12:13], 0, v152
	s_nop 1
	v_cndmask_b32_e64 v147, v147, v150, s[12:13]
	v_mul_f32_e32 v149, 0x37800000, v147
	v_cndmask_b32_e32 v147, v147, v149, vcc
	v_cmp_class_f32_e32 vcc, v146, v234
	s_nop 1
	v_cndmask_b32_e32 v146, v147, v146, vcc
	v_div_scale_f32 v147, s[12:13], v146, v146, 1.0
	v_rcp_f32_e32 v149, v147
	v_div_scale_f32 v150, vcc, 1.0, v146, 1.0
	v_fma_f32 v151, -v147, v149, 1.0
	v_fmac_f32_e32 v149, v151, v149
	v_mul_f32_e32 v151, v150, v149
	v_fma_f32 v152, -v147, v151, v150
	v_fmac_f32_e32 v151, v152, v149
	v_fma_f32 v147, -v147, v151, v150
	v_div_fmas_f32 v147, v147, v149, v151
	v_div_fixup_f32 v146, v147, v146, 1.0
	v_lshl_add_u32 v147, v148, 2, s84
	ds_write_b32 v147, v146 offset:4096

; #define PG8_LAS __attribute__((address_space(3)))
;     __device__ __forceinline__ void operator()(const f32x4 (&acc)[2][2][4][2], const Unit& u, int wr, int wc, int fr, int fq) const {
;     ...
;         asm volatile("s_waitcnt lgkmcnt(0)" ::: "memory"); __builtin_amdgcn_s_barrier(); asm volatile("" ::: "memory");
;         const int tid = (wr * 4 + wc) * 64 + fq * 16 + fr;
;         if (tid < 256) { const f32x4 p = *(const PG8_LAS f32x4*)(P + tid * 4); __hip_atomic_store(ssq + (size_t)(u.pm * BM + tid) * 4 + u.pn, (p[0] + p[1]) + (p[2] + p[3]), __ATOMIC_RELAXED, __HIP_MEMORY_SCOPE_AGENT); }
;         asm volatile("s_waitcnt vmcnt(0)" ::: "memory"); __builtin_amdgcn_s_barrier(); asm volatile("" ::: "memory");
;         unsigned* pc = cnt + u.pm * 64;
;         if (tid == 0) __hip_atomic_fetch_add(pc, 1u, __ATOMIC_RELAXED, __HIP_MEMORY_SCOPE_AGENT);
;         if (tid < 64) { unsigned sp = 0u;
;             while (__hip_atomic_load(pc, __ATOMIC_RELAXED, __HIP_MEMORY_SCOPE_AGENT) < 4u) { __builtin_amdgcn_s_sleep(2); if (++sp > (1u << 20)) { if (tid == 0) __hip_atomic_store(tmo, 1u, __ATOMIC_RELAXED, __HIP_MEMORY_SCOPE_AGENT); break; } } }
;         asm volatile("s_waitcnt vmcnt(0)" ::: "memory"); __builtin_amdgcn_s_barrier(); asm volatile("" ::: "memory");
.LBB0_1621:
	s_or_b64 exec, exec, s[70:71]
	s_and_saveexec_b64 s[14:15], s[12:13]
	s_cbranch_execz .LBB0_1643
	v_lshl_add_u64 v[146:147], v[146:147], 4, s[44:45]
	s_mov_b32 s24, 0x40000

;     __device__ __forceinline__ void operator()(const f32x4 (&acc)[2][2][4][2], const Unit& u, int wr, int wc, int fr, int fq) const {
;     ...
;         if (tid < 256) { const float* sp4 = ssq + (size_t)(u.pm * BM + tid) * 4;
;             const float t = (__hip_atomic_load(sp4, __ATOMIC_RELAXED, __HIP_MEMORY_SCOPE_AGENT) + __hip_atomic_load(sp4 + 1, __ATOMIC_RELAXED, __HIP_MEMORY_SCOPE_AGENT))
;                           + (__hip_atomic_load(sp4 + 2, __ATOMIC_RELAXED, __HIP_MEMORY_SCOPE_AGENT) + __hip_atomic_load(sp4 + 3, __ATOMIC_RELAXED, __HIP_MEMORY_SCOPE_AGENT));
;             P[1024 + tid] = 1.f / sqrtf(t * (1.f / DM) + EPS); }
.Lx10_ready:
	s_mov_b32 s8, 0xf800000
	s_waitcnt vmcnt(0)
	v_pk_add_f32 v[146:147], v[150:151], v[152:153]
	s_nop 0
	v_add_f32_e32 v146, v146, v147
	v_fmamk_f32 v146, v146, 0x3a800000, v188
	v_mul_f32_e32 v147, 0x4f800000, v146
	v_cmp_gt_f32_e32 vcc, s8, v146
	s_nop 1
	v_cndmask_b32_e32 v146, v146, v147, vcc
	v_sqrt_f32_e32 v147, v146
	s_nop 0
	v_add_u32_e32 v149, -1, v147
	v_add_u32_e32 v150, 1, v147
	v_fma_f32 v151, -v149, v147, v146
	v_fma_f32 v152, -v150, v147, v146
	v_cmp_ge_f32_e64 s[12:13], 0, v151
	s_nop 1
	v_cndmask_b32_e64 v147, v147, v149, s[12:13]
	v_cmp_lt_f32_e64 s[12:13], 0, v152
	s_nop 1
	v_cndmask_b32_e64 v147, v147, v150, s[12:13]
	v_mul_f32_e32 v149, 0x37800000, v147
	v_cndmask_b32_e32 v147, v147, v149, vcc
	v_cmp_class_f32_e32 vcc, v146, v189
	s_nop 1
	v_cndmask_b32_e32 v146, v147, v146, vcc
	v_div_scale_f32 v147, s[12:13], v146, v146, 1.0
	v_rcp_f32_e32 v149, v147
	v_div_scale_f32 v150, vcc, 1.0, v146, 1.0
	v_fma_f32 v151, -v147, v149, 1.0
	v_fmac_f32_e32 v149, v151, v149
	v_mul_f32_e32 v151, v150, v149
	v_fma_f32 v152, -v147, v151, v150
	v_fmac_f32_e32 v151, v152, v149
	v_fma_f32 v147, -v147, v151, v150
	v_div_fmas_f32 v147, v147, v149, v151
	v_div_fixup_f32 v146, v147, v146, 1.0
	v_lshl_add_u32 v147, v148, 2, s84
	ds_write_b32 v147, v146 offset:4096
